# same as previous plus mid-way trampolines for the four branches that span the whole layer loop (code-size headroom only)
# speedup vs baseline: 1.0524x; 1.0011x over previous
; DI void prep_phase(const Params& p, int l, char* smem, const bool dry = false) {
;     ...
;       __syncthreads();
;       for (int c = tid; c < DSH; c += 256) rows[c] = rows[8 * DSH + c];
.LBB0_1211:
	ds_read_b32 v40, v38 offset:53248
	v_add_u32_e32 v39, 0x100, v39
	v_cmp_lt_i32_e32 vcc, s66, v39
	s_or_b64 s[20:21], vcc, s[20:21]
	s_waitcnt lgkmcnt(0)
	ds_write_b32 v38, v40
	v_add_u32_e32 v38, 0x400, v38
	s_andn2_b64 exec, exec, s[20:21]
	s_cbranch_execnz .LBB0_1211
	s_branch .LBB0_1164
.Ltramp_131:
	s_branch .LBB0_131

; DI int otid() { int t = __builtin_amdgcn_workitem_id_x(); asm volatile("" : "+v"(t)); return t; }
; DI void gbar(GBar& g) {
;   g.k++;
;   asm volatile("s_waitcnt vmcnt(0) lgkmcnt(0)" ::: "memory");
;   __syncthreads();
;   if (otid() == 0) {
;     const unsigned a = __hip_atomic_fetch_add(&g.w[1152 + 64 * g.xcc], 1u, __ATOMIC_RELAXED, __HIP_MEMORY_SCOPE_AGENT) + 1u;
.Ltramp_1875:
	s_branch .LBB0_1875
.LBB0_1212:
	s_waitcnt vmcnt(0) lgkmcnt(0)
	v_mov_b32_e32 v4, v182
	s_waitcnt lgkmcnt(0)
	s_barrier
	s_nop 0
	v_cmp_eq_u32_e32 vcc, 0, v4
	s_and_saveexec_b64 s[4:5], vcc
	s_cbranch_execz .LBB0_1221
	s_mov_b64 s[8:9], exec
	v_mbcnt_lo_u32_b32 v4, s8, 0
	v_mbcnt_hi_u32_b32 v4, s9, v4
	v_cmp_eq_u32_e32 vcc, 0, v4
	s_and_saveexec_b64 s[6:7], vcc
	s_cbranch_execz .LBB0_1215
	s_bcnt1_i32_b64 s8, s[8:9]
	v_mov_b32_e32 v5, s8
	v_readlane_b32 s8, v254, 14
	v_readlane_b32 s9, v254, 15
	s_nop 4
	global_atomic_add v5, v164, v5, s[8:9] sc0
